# guide 7.12: the wave-uniform block-diagonal test in the mix GEMM-unit K-loop shortened from a 7-instruction ballot to v_cmp + s_cmp
# speedup vs baseline: 1.0024x; 1.0005x over previous
.LBB0_1076:
	s_add_i32 s35, s44, 0x10000
	s_and_b32 s4, s35, 0x10000
	s_add_i32 s17, s4, 32
	v_add_u32_e32 v2, s17, v163
	v_add_u32_e32 v3, 0x8000, v2
	v_readfirstlane_b32 s4, v2
	v_lshl_add_u64 v[0:1], v[134:135], 0, s[70:71]
	s_mov_b32 m0, s4
	v_readfirstlane_b32 s4, v3
	v_add_u32_e32 v3, 0x2000, v2
	global_load_lds_dwordx4 v[0:1], off
	v_lshl_add_u64 v[0:1], v[150:151], 0, s[70:71]
	s_mov_b32 m0, s4
	v_readfirstlane_b32 s4, v3
	v_add_u32_e32 v3, 0xa000, v2
	global_load_lds_dwordx4 v[0:1], off
	v_lshl_add_u64 v[0:1], v[136:137], 0, s[70:71]
	s_mov_b32 m0, s4
	v_readfirstlane_b32 s4, v3
	v_add_u32_e32 v3, 0x4000, v2
	global_load_lds_dwordx4 v[0:1], off
	v_lshl_add_u64 v[0:1], v[152:153], 0, s[70:71]
	s_mov_b32 m0, s4
	v_readfirstlane_b32 s4, v3
	v_add_u32_e32 v3, 0xc000, v2
	global_load_lds_dwordx4 v[0:1], off
	v_lshl_add_u64 v[0:1], v[146:147], 0, s[70:71]
	s_mov_b32 m0, s4
	v_readfirstlane_b32 s4, v3
	v_add_u32_e32 v3, 0x6000, v2
	global_load_lds_dwordx4 v[0:1], off
	v_lshl_add_u64 v[0:1], v[154:155], 0, s[70:71]
	s_mov_b32 m0, s4
	v_readfirstlane_b32 s4, v3
	v_add_u32_e32 v2, 0xe000, v2
	global_load_lds_dwordx4 v[0:1], off
	v_lshl_add_u64 v[0:1], v[148:149], 0, s[70:71]
	s_mov_b32 m0, s4
	v_readfirstlane_b32 s4, v2
	global_load_lds_dwordx4 v[0:1], off
	v_lshl_add_u64 v[0:1], v[156:157], 0, s[70:71]
	s_mov_b32 m0, s4
	s_andn2_b64 vcc, exec, s[74:75]
	global_load_lds_dwordx4 v[0:1], off
	v_cndmask_b32_e64 v0, 0, 1, s[74:75]
	v_cmp_ne_u32_e64 s[4:5], 1, v0
	s_mov_b64 s[76:77], s[72:73]
	s_cbranch_vccnz .LBB0_1078
	s_lshr_b32 s45, s23, s18
	v_cmp_eq_u32_e32 vcc, s45, v160
	s_nop 0
	s_cmp_lg_u64 vcc, 0
	s_cselect_b64 s[76:77], -1, 0

.LBB0_1082:
	s_and_b64 vcc, exec, s[4:5]
	s_cbranch_vccnz .LBB0_1084
	s_add_i32 s4, s22, 1
	s_lshr_b32 s4, s4, s18
	v_cmp_eq_u32_e32 vcc, s4, v160
	s_nop 0
	s_cmp_lg_u64 vcc, 0
	s_cselect_b64 s[72:73], -1, 0
